# S5 prompt item: Lambda^T of the carry step requested with the first loads; carry wave does not wait for a round trip before its chain
# speedup vs baseline: 1.0011x; 1.0011x over previous
; #define LAS __attribute__((address_space(3)))
; #define S5_LAUNDER() int tid_ = tid0, lane_ = lane0; asm volatile("" : "+v"(tid_), "+v"(lane_)); const int tid = tid_, lane = lane_, fr = lane & 15, fq = lane >> 4; (void)tid; (void)fr; (void)fq
; __device__ __forceinline__ void s5_prompt_item_mfma(LAS unsigned char* lds, int tid0, int lane0, int wave, int n, int g, const bf16* USg, const bf16* FTg, const bf16* WTg, const bf16* GTg, ...
;     ...
;     { S5_LAUNDER(); const bf16* usrc = USg + ((size_t)g * M + (size_t)n * SEQ) * 16;
; #pragma unroll
;       for (int it = 0; it < 8; ++it) { const int q = tid + 512 * it, token = q >> 1, half = q & 1; const v4u v = *(const v4u*)(usrc + (size_t)token * 16 + 8 * half);
;           *(LAS v4u*)(lds + U_OFF + (token >> 5) * 1056 + (token & 31) * 32 + 16 * half) = v; } }
;     bf16x8 wa[16];
;     { S5_LAUNDER();
; #pragma unroll
;     for (int ks = 0; ks < 16; ++ks) wa[ks] = *(const bf16x8*)(WTg + ((size_t)(wave * 16 + ks) * 64 + lane) * 8);
;     ...
;         const int p = tid; const float lr = ltp[2 * p], li = ltp[2 * p + 1]; float hr = 0.f, hi = 0.f;
.LBB0_848:
	s_and_b32 s65, s64, 31
	s_ashr_i32 s10, s64, 5
	s_lshl_b32 s8, s65, 15
	v_readlane_b32 s9, v254, 54
	s_add_u32 vcc_lo, s9, s8
	v_readlane_b32 s8, v254, 56
	s_addc_u32 vcc_hi, s8, 0
	s_lshl_b32 s8, s65, 17
	v_readlane_b32 s9, v253, 45
	s_add_u32 s72, s9, s8
	v_readlane_b32 s9, v253, 49
	s_addc_u32 s73, s9, 0
	v_readlane_b32 s9, v253, 51
	s_add_u32 s54, s9, s8
	v_readlane_b32 s8, v253, 55
	s_addc_u32 s55, s8, 0
	s_ashr_i32 s11, s10, 31
	s_mul_i32 s12, s65, 0x4200
	s_lshl_b64 s[8:9], s[10:11], 11
	s_add_u32 s12, s8, s12
	s_addc_u32 s13, s9, 0
	s_lshl_b64 s[12:13], s[12:13], 5
	s_mov_b32 s37, s74
	s_add_u32 s74, s74, s12
	s_mov_b32 s84, s75
	s_addc_u32 s75, s75, s13
	v_readlane_b32 s12, v252, 4
	v_readlane_b32 s13, v252, 5
	v_readlane_b32 s14, v252, 6
	v_readlane_b32 s15, v252, 7
	s_mov_b64 s[14:15], s[12:13]
	v_mov_b32_e32 v52, v192
	v_mov_b32_e32 v2, v196
	s_movk_i32 s11, 0x420
	v_ashrrev_i32_e32 v36, 1, v52
	v_ashrrev_i32_e32 v37, 31, v36
	s_waitcnt vmcnt(0)
	v_lshlrev_b64 v[4:5], 5, v[36:37]
	v_add_u32_e32 v37, 0x200, v52
	v_ashrrev_i32_e32 v38, 1, v37
	v_ashrrev_i32_e32 v39, 31, v38
	v_lshlrev_b64 v[6:7], 5, v[38:39]
	v_add_u32_e32 v39, 0x400, v52
	v_lshlrev_b32_e32 v2, 4, v52
	v_ashrrev_i32_e32 v40, 1, v39
	v_and_b32_e32 v2, 16, v2
	v_ashrrev_i32_e32 v41, 31, v40
	v_lshl_add_u64 v[32:33], s[74:75], 0, v[2:3]
	v_lshlrev_b64 v[12:13], 5, v[40:41]
	v_add_u32_e32 v41, 0x600, v52
	v_lshl_add_u64 v[4:5], v[32:33], 0, v[4:5]
	v_lshl_add_u64 v[8:9], v[32:33], 0, v[6:7]
	v_ashrrev_i32_e32 v42, 1, v41
	global_load_dwordx4 v[4:7], v[4:5], off
	s_nop 0
	global_load_dwordx4 v[8:11], v[8:9], off
	v_ashrrev_i32_e32 v43, 31, v42
	v_lshl_add_u64 v[12:13], v[32:33], 0, v[12:13]
	v_lshlrev_b64 v[16:17], 5, v[42:43]
	global_load_dwordx4 v[12:15], v[12:13], off
	v_lshl_add_u64 v[16:17], v[32:33], 0, v[16:17]
	v_add_u32_e32 v43, 0x800, v52
	global_load_dwordx4 v[16:19], v[16:17], off
	v_ashrrev_i32_e32 v44, 1, v43
	v_ashrrev_i32_e32 v45, 31, v44
	v_lshlrev_b64 v[20:21], 5, v[44:45]
	v_lshl_add_u64 v[20:21], v[32:33], 0, v[20:21]
	v_add_u32_e32 v45, 0xa00, v52
	global_load_dwordx4 v[20:23], v[20:21], off
	v_ashrrev_i32_e32 v46, 1, v45
	v_ashrrev_i32_e32 v47, 31, v46
	v_lshlrev_b64 v[24:25], 5, v[46:47]
	v_lshl_add_u64 v[24:25], v[32:33], 0, v[24:25]
	v_add_u32_e32 v47, 0xc00, v52
	global_load_dwordx4 v[24:27], v[24:25], off
	v_ashrrev_i32_e32 v48, 1, v47
	v_ashrrev_i32_e32 v49, 31, v48
	v_lshlrev_b64 v[28:29], 5, v[48:49]
	v_lshl_add_u64 v[28:29], v[32:33], 0, v[28:29]
	v_add_u32_e32 v49, 0xe00, v52
	global_load_dwordx4 v[28:31], v[28:29], off
	v_ashrrev_i32_e32 v50, 1, v49
	v_ashrrev_i32_e32 v51, 31, v50
	v_lshlrev_b64 v[34:35], 5, v[50:51]
	v_lshl_add_u64 v[32:33], v[32:33], 0, v[34:35]
	global_load_dwordx4 v[32:35], v[32:33], off
	v_mov_b32_e32 v156, v196
	v_ashrrev_i32_e32 v157, 31, v156
	v_lshl_add_u64 v[156:157], v[156:157], 4, s[72:73]
	v_readlane_b32 s72, v253, 41
	v_readlane_b32 s73, v253, 42
	s_nop 1
	v_lshl_add_u64 v[158:159], v[156:157], 0, s[72:73]
	global_load_dwordx4 v[164:167], v[158:159], off
	v_readlane_b32 s72, v253, 33
	v_readlane_b32 s73, v253, 34
	s_nop 1
	v_lshl_add_u64 v[158:159], v[156:157], 0, s[72:73]
	global_load_dwordx4 v[168:171], v[158:159], off
	v_readlane_b32 s72, v254, 23
	v_readlane_b32 s73, v254, 24
	s_nop 1
	v_lshl_add_u64 v[158:159], v[156:157], 0, s[72:73]
	v_readlane_b32 s72, v253, 43
	v_readlane_b32 s73, v253, 44
	s_nop 1
	v_lshl_add_u64 v[160:161], v[156:157], 0, s[72:73]
	global_load_dwordx4 v[176:179], v[158:159], off
	global_load_dwordx4 v[180:183], v[160:161], off
	v_readlane_b32 s72, v254, 46
	v_readlane_b32 s73, v254, 47
	s_nop 1
	v_lshl_add_u64 v[158:159], v[156:157], 0, s[72:73]
	v_readlane_b32 s72, v253, 31
	v_readlane_b32 s73, v253, 32
	s_nop 1
	v_lshl_add_u64 v[160:161], v[156:157], 0, s[72:73]
	v_readlane_b32 s72, v253, 35
	v_readlane_b32 s73, v253, 36
	global_load_dwordx4 v[184:187], v[158:159], off
	global_load_dwordx4 v[188:191], v[160:161], off
	v_lshl_add_u64 v[158:159], v[156:157], 0, s[72:73]
	v_readlane_b32 s72, v253, 37
	v_readlane_b32 s73, v253, 38
	s_nop 1
	v_lshl_add_u64 v[160:161], v[156:157], 0, s[72:73]
	v_readlane_b32 s72, v254, 19
	v_readlane_b32 s73, v254, 20
	global_load_dwordx4 v[212:215], v[158:159], off
	global_load_dwordx4 v[216:219], v[160:161], off
	v_lshl_add_u64 v[158:159], v[156:157], 0, s[72:73]
	v_readlane_b32 s72, v254, 48
	v_readlane_b32 s73, v254, 49
	s_nop 1
	v_lshl_add_u64 v[160:161], v[156:157], 0, s[72:73]
	v_readlane_b32 s72, v254, 50
	v_readlane_b32 s73, v254, 51
	global_load_dwordx4 v[220:223], v[158:159], off
	global_load_dwordx4 v[224:227], v[160:161], off
	v_lshl_add_u64 v[158:159], v[156:157], 0, s[72:73]
	v_readlane_b32 s72, v253, 39
	v_readlane_b32 s73, v253, 40
	s_nop 1
	v_lshl_add_u64 v[160:161], v[156:157], 0, s[72:73]
	v_readlane_b32 s72, v254, 52
	v_readlane_b32 s73, v254, 53
	global_load_dwordx4 v[228:231], v[158:159], off
	global_load_dwordx4 v[232:235], v[160:161], off
	v_lshl_add_u64 v[158:159], v[156:157], 0, s[72:73]
	v_lshl_add_u64 v[160:161], v[156:157], 0, s[80:81]
	global_load_dwordx4 v[236:239], v[158:159], off
	global_load_dwordx4 v[240:243], v[160:161], off
	v_lshl_add_u64 v[158:159], v[156:157], 0, s[76:77]
	v_lshl_add_u64 v[156:157], v[156:157], 0, s[30:31]
	global_load_dwordx4 v[198:201], v[158:159], off
	s_nop 0
	global_load_dwordx4 v[202:205], v[156:157], off
	v_readlane_b32 s72, v254, 32
	s_or_b32 s32, s72, s65
	s_mulk_i32 s32, 0x4200
	v_readlane_b32 s72, v253, 63
	v_readlane_b32 s73, v254, 1
	s_add_u32 s72, s72, s32
	s_addc_u32 s73, s73, 0
	v_lshlrev_b32_e32 v172, 1, v192
	v_ashrrev_i32_e32 v173, 31, v172
	v_lshl_add_u64 v[172:173], v[172:173], 2, s[72:73]
	global_load_dwordx2 v[162:163], v[172:173], off
	v_ashrrev_i32_e32 v51, 6, v52
	v_mul_lo_u32 v51, v51, s11
	v_lshlrev_b32_e32 v36, 5, v36
	v_ashrrev_i32_e32 v37, 6, v37
	v_ashrrev_i32_e32 v39, 6, v39
	v_add_u32_e32 v51, 0, v51
	v_and_b32_e32 v36, 0x3e0, v36
	v_mul_lo_u32 v37, v37, s11
	v_lshlrev_b32_e32 v38, 5, v38
	v_mul_lo_u32 v39, v39, s11
	v_lshlrev_b32_e32 v40, 5, v40
	v_ashrrev_i32_e32 v41, 6, v41
	v_add3_u32 v36, v51, v36, v2
	v_add_u32_e32 v37, 0, v37
	v_and_b32_e32 v38, 0x3e0, v38
	v_add_u32_e32 v39, 0, v39
	v_and_b32_e32 v40, 0x3e0, v40
	v_add3_u32 v37, v37, v38, v2
	v_add3_u32 v38, v39, v40, v2
	s_waitcnt vmcnt(24)
; #define LAS __attribute__((address_space(3)))
; #define S5_LAUNDER() int tid_ = tid0, lane_ = lane0; asm volatile("" : "+v"(tid_), "+v"(lane_)); const int tid = tid_, lane = lane_, fr = lane & 15, fq = lane >> 4; (void)tid; (void)fr; (void)fq
; __device__ __forceinline__ void s5_prompt_item_mfma(LAS unsigned char* lds, int tid0, int lane0, int wave, int n, int g, const bf16* USg, const bf16* FTg, const bf16* WTg, const bf16* GTg, ...
;     ...
;       for (int it = 0; it < 8; ++it) { const int q = tid + 512 * it, token = q >> 1, half = q & 1; const v4u v = *(const v4u*)(usrc + (size_t)token * 16 + 8 * half);
;           *(LAS v4u*)(lds + U_OFF + (token >> 5) * 1056 + (token & 31) * 32 + 16 * half) = v; } }
;     bf16x8 wa[16];
;     { S5_LAUNDER();
; #pragma unroll
;     for (int ks = 0; ks < 16; ++ks) wa[ks] = *(const bf16x8*)(WTg + ((size_t)(wave * 16 + ks) * 64 + lane) * 8);
;     }
;     __syncthreads();
;     {   S5_LAUNDER();
;         f32x4 accS[4];
; #pragma unroll
;         for (int cb = 0; cb < 4; ++cb) accS[cb] = (f32x4){0.f, 0.f, 0.f, 0.f};
; #pragma unroll
;         for (int ks = 0; ks < 16; ++ks) {
; #pragma unroll
;             for (int cb = 0; cb < 4; ++cb) { const bf16x8 b = *(const LAS bf16x8*)(lds + U_OFF + (16 * cb + fr) * 1056 + (2 * ks + (fq >> 1)) * 32 + 16 * (fq & 1));
;                 accS[cb] = __builtin_amdgcn_mfma_f32_16x16x32_bf16(wa[ks], b, accS[cb], 0, 0, 0); }
;             if (ks & 1) asm volatile("" ::: "memory"); }
	ds_write_b128 v36, v[4:7]
	s_waitcnt vmcnt(23)
	ds_write_b128 v37, v[8:11]
	s_waitcnt vmcnt(22)
	ds_write_b128 v38, v[12:15]
	v_mul_lo_u32 v4, v41, s11
	v_lshlrev_b32_e32 v5, 5, v42
	v_add_u32_e32 v4, 0, v4
	v_and_b32_e32 v5, 0x3e0, v5
	v_add3_u32 v4, v4, v5, v2
	s_waitcnt vmcnt(21)
	ds_write_b128 v4, v[16:19]
	v_ashrrev_i32_e32 v4, 6, v43
	v_mul_lo_u32 v4, v4, s11
	v_lshlrev_b32_e32 v5, 5, v44
	v_add_u32_e32 v4, 0, v4
	v_and_b32_e32 v5, 0x3e0, v5
	v_add3_u32 v4, v4, v5, v2
	s_waitcnt vmcnt(20)
	ds_write_b128 v4, v[20:23]
	v_ashrrev_i32_e32 v4, 6, v45
	v_mul_lo_u32 v4, v4, s11
	v_lshlrev_b32_e32 v5, 5, v46
	v_add_u32_e32 v4, 0, v4
	v_and_b32_e32 v5, 0x3e0, v5
	v_add3_u32 v4, v4, v5, v2
	s_waitcnt vmcnt(19)
	ds_write_b128 v4, v[24:27]
	v_ashrrev_i32_e32 v4, 6, v47
	v_mul_lo_u32 v4, v4, s11
	v_lshlrev_b32_e32 v5, 5, v48
	v_add_u32_e32 v4, 0, v4
	v_and_b32_e32 v5, 0x3e0, v5
	v_add3_u32 v4, v4, v5, v2
	s_waitcnt vmcnt(18)
	ds_write_b128 v4, v[28:31]
	v_ashrrev_i32_e32 v4, 6, v49
	v_mul_lo_u32 v4, v4, s11
	v_lshlrev_b32_e32 v5, 5, v50
	v_add_u32_e32 v4, 0, v4
	v_and_b32_e32 v5, 0x3e0, v5
	v_add3_u32 v2, v4, v5, v2
	s_waitcnt vmcnt(17)
	ds_write_b128 v2, v[32:35]
	v_mov_b32_e32 v2, v192
	v_mov_b32_e32 v4, v196
	v_mov_b32_e32 v48, v192
	v_mov_b32_e32 v2, v196
	s_movk_i32 s11, 0x4000
	s_waitcnt lgkmcnt(0)
	s_barrier
	s_nop 0
	v_and_b32_e32 v48, 15, v2
	v_and_b32_e32 v49, 0xffffffe0, v2
	v_add_u32_e32 v49, 0, v49
	v_and_b32_e32 v70, 16, v2
	v_mul_u32_u24_e32 v71, 0x420, v48
	v_add3_u32 v49, v49, v70, v71
	v_and_b32_e32 v2, -16, v2
	ds_read_b128 v[108:111], v49
	ds_read_b128 v[112:115], v49 offset:16896
	ds_read_b128 v[116:119], v49 offset:33792
	ds_read_b128 v[120:123], v49 offset:50688
	ds_read_b128 v[124:127], v49 offset:64
	ds_read_b128 v[128:131], v49 offset:16960
	ds_read_b128 v[132:135], v49 offset:33856
	ds_read_b128 v[136:139], v49 offset:50752
	ds_read_b128 v[140:143], v49 offset:128
	ds_read_b128 v[144:147], v49 offset:17024
	ds_read_b128 v[148:151], v49 offset:33920
	ds_read_b128 v[152:155], v49 offset:50816
	s_waitcnt vmcnt(16) lgkmcnt(8)
	v_mfma_f32_16x16x32_bf16 v[70:73], v[164:167], v[108:111], 0
	v_mfma_f32_16x16x32_bf16 v[74:77], v[164:167], v[112:115], 0
	v_mfma_f32_16x16x32_bf16 v[78:81], v[164:167], v[116:119], 0
	v_mfma_f32_16x16x32_bf16 v[82:85], v[164:167], v[120:123], 0
	ds_read_b128 v[108:111], v49 offset:192
	ds_read_b128 v[112:115], v49 offset:17088
	ds_read_b128 v[116:119], v49 offset:33984
	ds_read_b128 v[120:123], v49 offset:50880
	s_waitcnt vmcnt(15) lgkmcnt(8)
	v_mfma_f32_16x16x32_bf16 v[70:73], v[168:171], v[124:127], v[70:73]
	v_mfma_f32_16x16x32_bf16 v[74:77], v[168:171], v[128:131], v[74:77]
	v_mfma_f32_16x16x32_bf16 v[78:81], v[168:171], v[132:135], v[78:81]
	v_mfma_f32_16x16x32_bf16 v[82:85], v[168:171], v[136:139], v[82:85]
	ds_read_b128 v[124:127], v49 offset:256
	ds_read_b128 v[128:131], v49 offset:17152
	ds_read_b128 v[132:135], v49 offset:34048
	ds_read_b128 v[136:139], v49 offset:50944
	s_waitcnt vmcnt(14) lgkmcnt(8)
	v_mfma_f32_16x16x32_bf16 v[70:73], v[176:179], v[140:143], v[70:73]
	v_mfma_f32_16x16x32_bf16 v[74:77], v[176:179], v[144:147], v[74:77]
	v_mfma_f32_16x16x32_bf16 v[78:81], v[176:179], v[148:151], v[78:81]
	v_mfma_f32_16x16x32_bf16 v[82:85], v[176:179], v[152:155], v[82:85]
	ds_read_b128 v[140:143], v49 offset:320
	ds_read_b128 v[144:147], v49 offset:17216
	ds_read_b128 v[148:151], v49 offset:34112
	ds_read_b128 v[152:155], v49 offset:51008
	s_waitcnt vmcnt(13) lgkmcnt(8)
	v_mfma_f32_16x16x32_bf16 v[70:73], v[180:183], v[108:111], v[70:73]
	v_mfma_f32_16x16x32_bf16 v[74:77], v[180:183], v[112:115], v[74:77]
	v_mfma_f32_16x16x32_bf16 v[78:81], v[180:183], v[116:119], v[78:81]
	v_mfma_f32_16x16x32_bf16 v[82:85], v[180:183], v[120:123], v[82:85]
	ds_read_b128 v[108:111], v49 offset:384
	ds_read_b128 v[112:115], v49 offset:17280
	ds_read_b128 v[116:119], v49 offset:34176
	ds_read_b128 v[120:123], v49 offset:51072
	s_waitcnt vmcnt(12) lgkmcnt(8)
	v_mfma_f32_16x16x32_bf16 v[70:73], v[184:187], v[124:127], v[70:73]
	v_mfma_f32_16x16x32_bf16 v[74:77], v[184:187], v[128:131], v[74:77]
	v_mfma_f32_16x16x32_bf16 v[78:81], v[184:187], v[132:135], v[78:81]
	v_mfma_f32_16x16x32_bf16 v[82:85], v[184:187], v[136:139], v[82:85]
	ds_read_b128 v[124:127], v49 offset:448
	ds_read_b128 v[128:131], v49 offset:17344
	ds_read_b128 v[132:135], v49 offset:34240
	ds_read_b128 v[136:139], v49 offset:51136
	s_waitcnt vmcnt(11) lgkmcnt(8)
	v_mfma_f32_16x16x32_bf16 v[70:73], v[188:191], v[140:143], v[70:73]
	v_mfma_f32_16x16x32_bf16 v[74:77], v[188:191], v[144:147], v[74:77]
	v_mfma_f32_16x16x32_bf16 v[78:81], v[188:191], v[148:151], v[78:81]
	v_mfma_f32_16x16x32_bf16 v[82:85], v[188:191], v[152:155], v[82:85]
	ds_read_b128 v[140:143], v49 offset:512
	ds_read_b128 v[144:147], v49 offset:17408
	ds_read_b128 v[148:151], v49 offset:34304
	ds_read_b128 v[152:155], v49 offset:51200
	s_waitcnt vmcnt(10) lgkmcnt(8)
	v_mfma_f32_16x16x32_bf16 v[70:73], v[212:215], v[108:111], v[70:73]
	v_mfma_f32_16x16x32_bf16 v[74:77], v[212:215], v[112:115], v[74:77]
	v_mfma_f32_16x16x32_bf16 v[78:81], v[212:215], v[116:119], v[78:81]
	v_mfma_f32_16x16x32_bf16 v[82:85], v[212:215], v[120:123], v[82:85]
	ds_read_b128 v[108:111], v49 offset:576
	ds_read_b128 v[112:115], v49 offset:17472
	ds_read_b128 v[116:119], v49 offset:34368
	ds_read_b128 v[120:123], v49 offset:51264
	s_waitcnt vmcnt(9) lgkmcnt(8)
	v_mfma_f32_16x16x32_bf16 v[70:73], v[216:219], v[124:127], v[70:73]
	v_mfma_f32_16x16x32_bf16 v[74:77], v[216:219], v[128:131], v[74:77]
	v_mfma_f32_16x16x32_bf16 v[78:81], v[216:219], v[132:135], v[78:81]
	v_mfma_f32_16x16x32_bf16 v[82:85], v[216:219], v[136:139], v[82:85]
	ds_read_b128 v[124:127], v49 offset:640
	ds_read_b128 v[128:131], v49 offset:17536
	ds_read_b128 v[132:135], v49 offset:34432
	ds_read_b128 v[136:139], v49 offset:51328
	s_waitcnt vmcnt(8) lgkmcnt(8)
; #define LAS __attribute__((address_space(3)))
; __device__ __forceinline__ unsigned pk2(float lo, float hi) { unsigned r; asm("v_cvt_pk_bf16_f32 %0, %1, %2" : "=v"(r) : "v"(lo), "v"(hi)); return r; }
; #define S5_LAUNDER() int tid_ = tid0, lane_ = lane0; asm volatile("" : "+v"(tid_), "+v"(lane_)); const int tid = tid_, lane = lane_, fr = lane & 15, fq = lane >> 4; (void)tid; (void)fr; (void)fq
; __device__ __forceinline__ void s5_prompt_item_mfma(LAS unsigned char* lds, int tid0, int lane0, int wave, int n, int g, const bf16* USg, const bf16* FTg, const bf16* WTg, const bf16* GTg, ...
;     ...
;         for (int ks = 0; ks < 16; ++ks) {
; #pragma unroll
;             for (int cb = 0; cb < 4; ++cb) { const bf16x8 b = *(const LAS bf16x8*)(lds + U_OFF + (16 * cb + fr) * 1056 + (2 * ks + (fq >> 1)) * 32 + 16 * (fq & 1));
;                 accS[cb] = __builtin_amdgcn_mfma_f32_16x16x32_bf16(wa[ks], b, accS[cb], 0, 0, 0); }
;             if (ks & 1) asm volatile("" ::: "memory"); }
; #pragma unroll
;         for (int cb = 0; cb < 4; ++cb) *(LAS f32x4*)(lds + R2_OFF + ((16 * cb + fr) * 132 + 16 * wave + 4 * fq) * 4) = accS[cb];
;     }
;     __syncthreads();
;     const int tau0 = wave, tau1 = 15 - wave, tau2 = 16 + wave, tau3 = 31 - wave;
;     bf16x8 ga[4][4]; v4u ftq[4];
;     { S5_LAUNDER();
; #pragma unroll
;       for (int it = 0; it < 4; ++it) { const int q = tid + 512 * it; ftq[it] = *(const v4u*)(FTg + (size_t)q * 8); }
; #pragma unroll
;       for (int kk = 0; kk < 4; ++kk) { ga[0][kk] = *(const bf16x8*)(GTg + ((size_t)(tau0 * 4 + kk) * 64 + lane) * 8); ga[1][kk] = *(const bf16x8*)(GTg + ((size_t)(tau1 * 4 + kk) * 64 + lane) * 8);
;                                        ga[2][kk] = *(const bf16x8*)(GTg + ((size_t)(tau2 * 4 + kk) * 64 + lane) * 8); ga[3][kk] = *(const bf16x8*)(GTg + ((size_t)(tau3 * 4 + kk) * 64 + lane) * 8); } }
;     { S5_LAUNDER(); if (tid < 64) {
;         const int p = tid; const float lr = ltp[2 * p], li = ltp[2 * p + 1]; float hr = 0.f, hi = 0.f;
; #pragma unroll 8
;         for (int c = 0; c < S5NC; ++c) { *(LAS unsigned*)(lds + HP_OFF + c * 272 + 4 * p) = pk2(hr, hi);
;             const f32x2 sv = *(const LAS f32x2*)(lds + R2_OFF + (c * 132 + 2 * p) * 4);
;             const float nr = lr * hr - li * hi + sv.x, ni = lr * hi + li * hr + sv.y; hr = nr; hi = ni; }
	v_mfma_f32_16x16x32_bf16 v[70:73], v[220:223], v[140:143], v[70:73]
	v_mfma_f32_16x16x32_bf16 v[74:77], v[220:223], v[144:147], v[74:77]
	v_mfma_f32_16x16x32_bf16 v[78:81], v[220:223], v[148:151], v[78:81]
	v_mfma_f32_16x16x32_bf16 v[82:85], v[220:223], v[152:155], v[82:85]
	ds_read_b128 v[140:143], v49 offset:704
	ds_read_b128 v[144:147], v49 offset:17600
	ds_read_b128 v[148:151], v49 offset:34496
	ds_read_b128 v[152:155], v49 offset:51392
	s_waitcnt vmcnt(7) lgkmcnt(8)
	v_mfma_f32_16x16x32_bf16 v[70:73], v[224:227], v[108:111], v[70:73]
	v_mfma_f32_16x16x32_bf16 v[74:77], v[224:227], v[112:115], v[74:77]
	v_mfma_f32_16x16x32_bf16 v[78:81], v[224:227], v[116:119], v[78:81]
	v_mfma_f32_16x16x32_bf16 v[82:85], v[224:227], v[120:123], v[82:85]
	ds_read_b128 v[108:111], v49 offset:768
	ds_read_b128 v[112:115], v49 offset:17664
	ds_read_b128 v[116:119], v49 offset:34560
	ds_read_b128 v[120:123], v49 offset:51456
	s_waitcnt vmcnt(6) lgkmcnt(8)
	v_mfma_f32_16x16x32_bf16 v[70:73], v[228:231], v[124:127], v[70:73]
	v_mfma_f32_16x16x32_bf16 v[74:77], v[228:231], v[128:131], v[74:77]
	v_mfma_f32_16x16x32_bf16 v[78:81], v[228:231], v[132:135], v[78:81]
	v_mfma_f32_16x16x32_bf16 v[82:85], v[228:231], v[136:139], v[82:85]
	ds_read_b128 v[124:127], v49 offset:832
	ds_read_b128 v[128:131], v49 offset:17728
	ds_read_b128 v[132:135], v49 offset:34624
	ds_read_b128 v[136:139], v49 offset:51520
	s_waitcnt vmcnt(5) lgkmcnt(8)
	v_mfma_f32_16x16x32_bf16 v[70:73], v[232:235], v[140:143], v[70:73]
	v_mfma_f32_16x16x32_bf16 v[74:77], v[232:235], v[144:147], v[74:77]
	v_mfma_f32_16x16x32_bf16 v[78:81], v[232:235], v[148:151], v[78:81]
	v_mfma_f32_16x16x32_bf16 v[82:85], v[232:235], v[152:155], v[82:85]
	ds_read_b128 v[140:143], v49 offset:896
	ds_read_b128 v[144:147], v49 offset:17792
	ds_read_b128 v[148:151], v49 offset:34688
	ds_read_b128 v[152:155], v49 offset:51584
	s_waitcnt vmcnt(4) lgkmcnt(8)
	v_mfma_f32_16x16x32_bf16 v[70:73], v[236:239], v[108:111], v[70:73]
	v_mfma_f32_16x16x32_bf16 v[74:77], v[236:239], v[112:115], v[74:77]
	v_mfma_f32_16x16x32_bf16 v[78:81], v[236:239], v[116:119], v[78:81]
	v_mfma_f32_16x16x32_bf16 v[82:85], v[236:239], v[120:123], v[82:85]
	ds_read_b128 v[108:111], v49 offset:960
	ds_read_b128 v[112:115], v49 offset:17856
	ds_read_b128 v[116:119], v49 offset:34752
	ds_read_b128 v[120:123], v49 offset:51648
	s_waitcnt vmcnt(3) lgkmcnt(8)
	v_mfma_f32_16x16x32_bf16 v[70:73], v[240:243], v[124:127], v[70:73]
	v_mfma_f32_16x16x32_bf16 v[74:77], v[240:243], v[128:131], v[74:77]
	v_mfma_f32_16x16x32_bf16 v[78:81], v[240:243], v[132:135], v[78:81]
	v_mfma_f32_16x16x32_bf16 v[82:85], v[240:243], v[136:139], v[82:85]
	s_waitcnt vmcnt(2) lgkmcnt(4)
	v_mfma_f32_16x16x32_bf16 v[70:73], v[198:201], v[140:143], v[70:73]
	v_mfma_f32_16x16x32_bf16 v[74:77], v[198:201], v[144:147], v[74:77]
	v_mfma_f32_16x16x32_bf16 v[78:81], v[198:201], v[148:151], v[78:81]
	v_mfma_f32_16x16x32_bf16 v[82:85], v[198:201], v[152:155], v[82:85]
	s_waitcnt vmcnt(1) lgkmcnt(0)
	v_mfma_f32_16x16x32_bf16 v[70:73], v[202:205], v[108:111], v[70:73]
	v_mfma_f32_16x16x32_bf16 v[74:77], v[202:205], v[112:115], v[74:77]
	v_mfma_f32_16x16x32_bf16 v[78:81], v[202:205], v[116:119], v[78:81]
	v_mfma_f32_16x16x32_bf16 v[82:85], v[202:205], v[120:123], v[82:85]
	s_nop 7
	v_mul_u32_u24_e32 v8, 0x210, v48
	v_add3_u32 v2, s36, v2, v8
	ds_write_b128 v2, v[70:73]
	ds_write_b128 v2, v[74:77] offset:8448
	ds_write_b128 v2, v[78:81] offset:16896
	ds_write_b128 v2, v[82:85] offset:25344
	v_mov_b32_e32 v4, v192
	v_mov_b32_e32 v6, v196
	s_waitcnt lgkmcnt(0)
	s_barrier
	v_mov_b32_e32 v2, v196
	v_ashrrev_i32_e32 v5, 31, v4
	v_lshl_add_u64 v[4:5], v[4:5], 4, vcc
	v_add_co_u32_e32 v8, vcc, s33, v4
	v_ashrrev_i32_e32 v7, 31, v6
	s_nop 0
	v_addc_co_u32_e32 v9, vcc, 0, v5, vcc
	v_add_co_u32_e32 v10, vcc, s11, v4
	s_movk_i32 s11, 0x6000
	s_nop 0
	v_addc_co_u32_e32 v11, vcc, 0, v5, vcc
	v_add_co_u32_e32 v12, vcc, s11, v4
	v_lshl_add_u64 v[6:7], v[6:7], 4, s[54:55]
	s_nop 0
	v_addc_co_u32_e32 v13, vcc, 0, v5, vcc
	global_load_dwordx4 v[24:27], v[4:5], off
	global_load_dwordx4 v[28:31], v[8:9], off
	global_load_dwordx4 v[32:35], v[10:11], off
	global_load_dwordx4 v[36:39], v[12:13], off
	v_lshl_add_u64 v[4:5], v[6:7], 0, s[34:35]
	v_lshl_add_u64 v[8:9], v[6:7], 0, s[38:39]
	global_load_dwordx4 v[152:155], v[4:5], off
	global_load_dwordx4 v[124:127], v[8:9], off
	v_lshl_add_u64 v[4:5], v[6:7], 0, s[2:3]
	v_lshl_add_u64 v[8:9], v[6:7], 0, s[0:1]
	global_load_dwordx4 v[108:111], v[4:5], off
	global_load_dwordx4 v[16:19], v[8:9], off
	v_lshl_add_u64 v[4:5], v[6:7], 0, s[4:5]
	v_lshl_add_u64 v[8:9], v[6:7], 0, s[28:29]
	global_load_dwordx4 v[140:143], v[4:5], off
	global_load_dwordx4 v[128:131], v[8:9], off
	v_lshl_add_u64 v[4:5], v[6:7], 0, s[18:19]
	v_lshl_add_u64 v[8:9], v[6:7], 0, s[92:93]
	global_load_dwordx4 v[112:115], v[4:5], off
	global_load_dwordx4 v[12:15], v[8:9], off
	v_lshl_add_u64 v[4:5], v[6:7], 0, s[96:97]
	v_lshl_add_u64 v[8:9], v[6:7], 0, s[40:41]
	global_load_dwordx4 v[144:147], v[4:5], off
	global_load_dwordx4 v[132:135], v[8:9], off
	v_lshl_add_u64 v[4:5], v[6:7], 0, s[42:43]
	v_lshl_add_u64 v[8:9], v[6:7], 0, s[44:45]
	global_load_dwordx4 v[116:119], v[4:5], off
	s_nop 0
	global_load_dwordx4 v[8:11], v[8:9], off
	v_lshl_add_u64 v[4:5], v[6:7], 0, s[46:47]
	v_lshl_add_u64 v[20:21], v[6:7], 0, s[48:49]
	global_load_dwordx4 v[148:151], v[4:5], off
	global_load_dwordx4 v[136:139], v[20:21], off
	v_lshl_add_u64 v[4:5], v[6:7], 0, s[50:51]
	v_lshl_add_u64 v[6:7], v[6:7], 0, s[88:89]
	global_load_dwordx4 v[120:123], v[4:5], off
	s_nop 0
	global_load_dwordx4 v[4:7], v[6:7], off
	v_mov_b32_e32 v20, v192
	s_nop 0
	v_cmp_gt_i32_e32 vcc, 64, v20
	s_and_saveexec_b64 s[54:55], vcc
	s_cbranch_execz .LBB0_852
	v_readlane_b32 s72, v254, 32
	s_or_b32 s11, s72, s65
	s_mulk_i32 s11, 0x4200
	v_readlane_b32 s72, v253, 63
	v_readlane_b32 s73, v254, 33
	s_add_u32 s72, s72, s11
	v_readlane_b32 s11, v254, 1
	v_lshlrev_b32_e32 v22, 1, v20
	s_addc_u32 s73, s11, 0
	v_ashrrev_i32_e32 v23, 31, v22
	s_waitcnt vmcnt(20)
	v_mov_b64_e32 v[22:23], v[162:163]
	v_mov_b32_e32 v42, 0
	v_lshlrev_b32_e32 v2, 2, v20
	v_lshlrev_b32_e32 v21, 3, v20
	s_mov_b32 s11, 64
	v_mov_b32_e32 v43, v42
	v_pk_mov_b32 v[40:41], v[22:23], v[22:23] op_sel:[1,0]
	v_add_u32_e32 v84, 0x10800, v21
	ds_read_b64 v[68:69], v84
	ds_read_b64 v[70:71], v84 offset:528
	ds_read_b64 v[72:73], v84 offset:1056
	ds_read_b64 v[74:75], v84 offset:1584
	ds_read_b64 v[76:77], v84 offset:2112
	ds_read_b64 v[78:79], v84 offset:2640
	ds_read_b64 v[80:81], v84 offset:3168
	ds_read_b64 v[82:83], v84 offset:3696
